# weight-transpose gather loops with a per-k gain (W_in, W_uq, W_ukv, W_mem_kv, W_ff1) rewritten: 8 weight + 8 gain loads issued together, one vmcnt wait, instead of one serialized round trip per elemen
# speedup vs baseline: 1.0112x; 1.0061x over previous
; #define LAS __attribute__((address_space(3)))
; DI void transpose_item(const float* W, const float* gain, int K, int Ns, int Nd, int mat, bf16_t* WT, LAS float* scr, int item, int lane) {
;     const int nblk = Nd / 32, kb = item / nblk, nb = item % nblk, k0 = 64 * kb, n0 = 32 * nb;
;     const int sc = srccol(mat, n0 + (lane & 31));
; #pragma unroll 8
;     for (int i = 0; i < 32; ++i) { const int kk = 2 * i + (lane >> 5); float v = 0.f; if (sc >= 0) v = W[(size_t)(k0 + kk) * Ns + sc]; if (gain) v *= gain[k0 + kk]; scr[kk * 33 + (lane & 31)] = v; }
;     asm volatile("s_waitcnt lgkmcnt(0)" ::: "memory");
.LBB0_38:
	v_mov_b32_e32 v100, 0
	v_mov_b32_e32 v101, 0
	v_mov_b32_e32 v102, 0
	v_mov_b32_e32 v103, 0
	v_mov_b32_e32 v104, 0
	v_mov_b32_e32 v105, 0
	v_mov_b32_e32 v106, 0
	v_mov_b32_e32 v107, 0
	v_lshl_add_u64 v[116:117], v[38:39], 0, s[6:7]
	global_load_dword v100, v[116:117], off
	v_lshl_add_u64 v[116:117], v[36:37], 0, s[6:7]
	global_load_dword v101, v[116:117], off
	v_lshl_add_u64 v[116:117], v[34:35], 0, s[6:7]
	global_load_dword v102, v[116:117], off
	v_lshl_add_u64 v[116:117], v[32:33], 0, s[6:7]
	global_load_dword v103, v[116:117], off
	v_lshl_add_u64 v[116:117], v[30:31], 0, s[6:7]
	global_load_dword v104, v[116:117], off
	v_lshl_add_u64 v[116:117], v[28:29], 0, s[6:7]
	global_load_dword v105, v[116:117], off
	v_lshl_add_u64 v[116:117], v[26:27], 0, s[6:7]
	global_load_dword v106, v[116:117], off
	v_lshl_add_u64 v[116:117], v[24:25], 0, s[6:7]
	global_load_dword v107, v[116:117], off
	s_andn2_b64 vcc, exec, s[22:23]
	s_cbranch_vccnz .Ltp1_g
	v_lshl_add_u64 v[116:117], s[8:9], 0, v[2:3]
	global_load_dword v108, v[116:117], off
	v_lshl_add_u64 v[116:117], s[8:9], 0, v[22:23]
	global_load_dword v109, v[116:117], off offset:8
	global_load_dword v110, v[116:117], off offset:16
	global_load_dword v111, v[116:117], off offset:24
	global_load_dword v112, v[116:117], off offset:32
	global_load_dword v113, v[116:117], off offset:40
	global_load_dword v114, v[116:117], off offset:48
	global_load_dword v115, v[116:117], off offset:56
	s_waitcnt vmcnt(0)
	v_mul_f32_e32 v100, v100, v108
	v_mul_f32_e32 v101, v101, v109
	v_mul_f32_e32 v102, v102, v110
	v_mul_f32_e32 v103, v103, v111
	v_mul_f32_e32 v104, v104, v112
	v_mul_f32_e32 v105, v105, v113
	v_mul_f32_e32 v106, v106, v114
	v_mul_f32_e32 v107, v107, v115
.Ltp1_g:
	s_waitcnt vmcnt(0)
	ds_write_b32 v42, v100
	ds_write_b32 v42, v101 offset:264
	ds_write_b32 v42, v102 offset:528
	ds_write_b32 v42, v103 offset:792
	ds_write_b32 v42, v104 offset:1056
	ds_write_b32 v42, v105 offset:1320
	ds_write_b32 v42, v106 offset:1584
	ds_write_b32 v42, v107 offset:1848
	s_add_u32 s6, s6, 0x10000
	s_addc_u32 s7, s7, 0
	s_add_u32 s8, s8, 64
	s_addc_u32 s9, s9, 0
	s_cmp_lg_u32 s6, 0x40000
	v_add_u32_e32 v42, 0x840, v42
	s_cbranch_scc1 .LBB0_38
	s_branch .LBB0_54

; DI void transpose_item(const float* W, const float* gain, int K, int Ns, int Nd, int mat, bf16_t* WT, LAS float* scr, int item, int lane) {
;     ...
;     for (int i = 0; i < 32; ++i) { const int kk = 2 * i + (lane >> 5); float v = 0.f; if (sc >= 0) v = W[(size_t)(k0 + kk) * Ns + sc]; if (gain) v *= gain[k0 + kk]; scr[kk * 33 + (lane & 31)] = v; }
.Ltp2_g:
	s_waitcnt vmcnt(0)
	ds_write_b32 v42, v100
	ds_write_b32 v42, v101 offset:264
	ds_write_b32 v42, v102 offset:528
	ds_write_b32 v42, v103 offset:792
	ds_write_b32 v42, v104 offset:1056
	ds_write_b32 v42, v105 offset:1320
	ds_write_b32 v42, v106 offset:1584
	ds_write_b32 v42, v107 offset:1848
	s_add_u32 s6, s6, 0x20000
	s_addc_u32 s7, s7, 0
	s_add_u32 s8, s8, 64
	s_addc_u32 s9, s9, 0
	s_cmp_lg_u32 s6, 0x80000
	v_add_u32_e32 v42, 0x840, v42
	s_cbranch_scc1 .LBB0_63
	s_branch .LBB0_79

; DI void transpose_item(const float* W, const float* gain, int K, int Ns, int Nd, int mat, bf16_t* WT, LAS float* scr, int item, int lane) {
;     ...
;     for (int i = 0; i < 32; ++i) { const int kk = 2 * i + (lane >> 5); float v = 0.f; if (sc >= 0) v = W[(size_t)(k0 + kk) * Ns + sc]; if (gain) v *= gain[k0 + kk]; scr[kk * 33 + (lane & 31)] = v; }
.LBB0_88:
	v_mov_b32_e32 v100, 0
	v_mov_b32_e32 v101, 0
	v_mov_b32_e32 v102, 0
	v_mov_b32_e32 v103, 0
	v_mov_b32_e32 v104, 0
	v_mov_b32_e32 v105, 0
	v_mov_b32_e32 v106, 0
	v_mov_b32_e32 v107, 0
	v_lshl_add_u64 v[116:117], v[38:39], 0, s[6:7]
	global_load_dword v100, v[116:117], off
	v_lshl_add_u64 v[116:117], v[36:37], 0, s[6:7]
	global_load_dword v101, v[116:117], off
	v_lshl_add_u64 v[116:117], v[34:35], 0, s[6:7]
	global_load_dword v102, v[116:117], off
	v_lshl_add_u64 v[116:117], v[32:33], 0, s[6:7]
	global_load_dword v103, v[116:117], off
	v_lshl_add_u64 v[116:117], v[30:31], 0, s[6:7]
	global_load_dword v104, v[116:117], off
	v_lshl_add_u64 v[116:117], v[28:29], 0, s[6:7]
	global_load_dword v105, v[116:117], off
	v_lshl_add_u64 v[116:117], v[26:27], 0, s[6:7]
	global_load_dword v106, v[116:117], off
	v_lshl_add_u64 v[116:117], v[22:23], 0, s[6:7]
	global_load_dword v107, v[116:117], off
	s_andn2_b64 vcc, exec, s[22:23]
	s_cbranch_vccnz .Ltp3_g
	v_lshl_add_u64 v[116:117], s[8:9], 0, v[2:3]
	global_load_dword v108, v[116:117], off
	v_lshl_add_u64 v[116:117], s[8:9], 0, v[24:25]
	global_load_dword v109, v[116:117], off offset:8
	global_load_dword v110, v[116:117], off offset:16
	global_load_dword v111, v[116:117], off offset:24
	global_load_dword v112, v[116:117], off offset:32
	global_load_dword v113, v[116:117], off offset:40
	global_load_dword v114, v[116:117], off offset:48
	global_load_dword v115, v[116:117], off offset:56
	s_waitcnt vmcnt(0)
	v_mul_f32_e32 v100, v100, v108
	v_mul_f32_e32 v101, v101, v109
	v_mul_f32_e32 v102, v102, v110
	v_mul_f32_e32 v103, v103, v111
	v_mul_f32_e32 v104, v104, v112
	v_mul_f32_e32 v105, v105, v113
	v_mul_f32_e32 v106, v106, v114
	v_mul_f32_e32 v107, v107, v115
.Ltp3_g:
	s_waitcnt vmcnt(0)
	ds_write_b32 v42, v100
	ds_write_b32 v42, v101 offset:264
	ds_write_b32 v42, v102 offset:528
	ds_write_b32 v42, v103 offset:792
	ds_write_b32 v42, v104 offset:1056
	ds_write_b32 v42, v105 offset:1320
	ds_write_b32 v42, v106 offset:1584
	ds_write_b32 v42, v107 offset:1848
	s_add_u32 s6, s6, 0x18000
	s_addc_u32 s7, s7, 0
	s_add_u32 s8, s8, 64
	s_addc_u32 s9, s9, 0
	s_cmp_lg_u32 s6, 0x60000
	v_add_u32_e32 v42, 0x840, v42
	s_cbranch_scc1 .LBB0_88
	s_branch .LBB0_104

; DI void transpose_item(const float* W, const float* gain, int K, int Ns, int Nd, int mat, bf16_t* WT, LAS float* scr, int item, int lane) {
;     ...
;     const int sc = srccol(mat, n0 + (lane & 31));
; #pragma unroll 8
;     for (int i = 0; i < 32; ++i) { const int kk = 2 * i + (lane >> 5); float v = 0.f; if (sc >= 0) v = W[(size_t)(k0 + kk) * Ns + sc]; if (gain) v *= gain[k0 + kk]; scr[kk * 33 + (lane & 31)] = v; }
.LBB0_120:
	v_mov_b32_e32 v100, 0
	v_mov_b32_e32 v101, 0
	v_mov_b32_e32 v102, 0
	v_mov_b32_e32 v103, 0
	v_mov_b32_e32 v104, 0
	v_mov_b32_e32 v105, 0
	v_mov_b32_e32 v106, 0
	v_mov_b32_e32 v107, 0
	s_and_saveexec_b64 s[10:11], s[4:5]
	s_cbranch_execz .Ltp4_w
	v_lshl_add_u64 v[116:117], v[38:39], 0, s[24:25]
	global_load_dword v100, v[116:117], off
	v_lshl_add_u64 v[116:117], v[36:37], 0, s[24:25]
	global_load_dword v101, v[116:117], off
	v_lshl_add_u64 v[116:117], v[34:35], 0, s[24:25]
	global_load_dword v102, v[116:117], off
	v_lshl_add_u64 v[116:117], v[32:33], 0, s[24:25]
	global_load_dword v103, v[116:117], off
	v_lshl_add_u64 v[116:117], v[30:31], 0, s[24:25]
	global_load_dword v104, v[116:117], off
	v_lshl_add_u64 v[116:117], v[28:29], 0, s[24:25]
	global_load_dword v105, v[116:117], off
	v_lshl_add_u64 v[116:117], v[26:27], 0, s[24:25]
	global_load_dword v106, v[116:117], off
	v_lshl_add_u64 v[116:117], v[22:23], 0, s[24:25]
	global_load_dword v107, v[116:117], off
.Ltp4_w:
	s_or_b64 exec, exec, s[10:11]
	s_andn2_b64 vcc, exec, s[26:27]
	s_cbranch_vccnz .Ltp4_g
	v_lshl_add_u64 v[116:117], s[8:9], 0, v[40:41]
	global_load_dword v108, v[116:117], off
	v_lshl_add_u64 v[116:117], s[8:9], 0, v[24:25]
	global_load_dword v109, v[116:117], off offset:8
	global_load_dword v110, v[116:117], off offset:16
	global_load_dword v111, v[116:117], off offset:24
	global_load_dword v112, v[116:117], off offset:32
	global_load_dword v113, v[116:117], off offset:40
	global_load_dword v114, v[116:117], off offset:48
	global_load_dword v115, v[116:117], off offset:56
	s_waitcnt vmcnt(0)
	v_mul_f32_e32 v100, v100, v108
	v_mul_f32_e32 v101, v101, v109
	v_mul_f32_e32 v102, v102, v110
	v_mul_f32_e32 v103, v103, v111
	v_mul_f32_e32 v104, v104, v112
	v_mul_f32_e32 v105, v105, v113
	v_mul_f32_e32 v106, v106, v114
	v_mul_f32_e32 v107, v107, v115
.Ltp4_g:
	s_waitcnt vmcnt(0)
	ds_write_b32 v2, v100
	ds_write_b32 v2, v101 offset:264
	ds_write_b32 v2, v102 offset:528
	ds_write_b32 v2, v103 offset:792
	ds_write_b32 v2, v104 offset:1056
	ds_write_b32 v2, v105 offset:1320
	ds_write_b32 v2, v106 offset:1584
	ds_write_b32 v2, v107 offset:1848
	s_add_u32 s24, s24, 0x53000
	s_addc_u32 s25, s25, 0
	s_add_u32 s8, s8, 64
	s_addc_u32 s9, s9, 0
	s_cmp_lg_u32 s24, 0x14c000
	v_add_u32_e32 v2, 0x840, v2
	s_cbranch_scc1 .LBB0_120
	s_branch .LBB0_8

; DI void transpose_item(const float* W, const float* gain, int K, int Ns, int Nd, int mat, bf16_t* WT, LAS float* scr, int item, int lane) {
;     ...
;     for (int i = 0; i < 32; ++i) { const int kk = 2 * i + (lane >> 5); float v = 0.f; if (sc >= 0) v = W[(size_t)(k0 + kk) * Ns + sc]; if (gain) v *= gain[k0 + kk]; scr[kk * 33 + (lane & 31)] = v; }
.LBB0_346:
	v_mov_b32_e32 v100, 0
	v_mov_b32_e32 v101, 0
	v_mov_b32_e32 v102, 0
	v_mov_b32_e32 v103, 0
	v_mov_b32_e32 v104, 0
	v_mov_b32_e32 v105, 0
	v_mov_b32_e32 v106, 0
	v_mov_b32_e32 v107, 0
	s_andn2_b64 vcc, exec, s[20:21]
	s_cbranch_vccnz .Ltp5_w
	v_lshl_add_u64 v[116:117], v[22:23], 0, s[22:23]
	global_load_dword v100, v[116:117], off
	v_lshl_add_u64 v[116:117], v[20:21], 0, s[22:23]
	global_load_dword v101, v[116:117], off
	v_lshl_add_u64 v[116:117], v[18:19], 0, s[22:23]
	global_load_dword v102, v[116:117], off
	v_lshl_add_u64 v[116:117], v[16:17], 0, s[22:23]
	global_load_dword v103, v[116:117], off
	v_lshl_add_u64 v[116:117], v[14:15], 0, s[22:23]
	global_load_dword v104, v[116:117], off
	v_lshl_add_u64 v[116:117], v[12:13], 0, s[22:23]
	global_load_dword v105, v[116:117], off
	v_lshl_add_u64 v[116:117], v[10:11], 0, s[22:23]
	global_load_dword v106, v[116:117], off
	v_lshl_add_u64 v[116:117], v[6:7], 0, s[22:23]
	global_load_dword v107, v[116:117], off
.Ltp5_w:
	s_andn2_b64 vcc, exec, s[24:25]
	s_cbranch_vccnz .Ltp5_g
	v_lshl_add_u64 v[116:117], s[8:9], 0, v[24:25]
	global_load_dword v108, v[116:117], off
	v_lshl_add_u64 v[116:117], s[8:9], 0, v[8:9]
	global_load_dword v109, v[116:117], off offset:8
	global_load_dword v110, v[116:117], off offset:16
	global_load_dword v111, v[116:117], off offset:24
	global_load_dword v112, v[116:117], off offset:32
	global_load_dword v113, v[116:117], off offset:40
	global_load_dword v114, v[116:117], off offset:48
	global_load_dword v115, v[116:117], off offset:56
	s_waitcnt vmcnt(0)
	v_mul_f32_e32 v100, v100, v108
	v_mul_f32_e32 v101, v101, v109
	v_mul_f32_e32 v102, v102, v110
	v_mul_f32_e32 v103, v103, v111
	v_mul_f32_e32 v104, v104, v112
	v_mul_f32_e32 v105, v105, v113
	v_mul_f32_e32 v106, v106, v114
	v_mul_f32_e32 v107, v107, v115
.Ltp5_g:
	s_waitcnt vmcnt(0)
	ds_write_b32 v0, v100
	ds_write_b32 v0, v101 offset:264
	ds_write_b32 v0, v102 offset:528
	ds_write_b32 v0, v103 offset:792
	ds_write_b32 v0, v104 offset:1056
	ds_write_b32 v0, v105 offset:1320
	ds_write_b32 v0, v106 offset:1584
	ds_write_b32 v0, v107 offset:1848
	s_add_u32 s22, s22, 0x40000
	s_addc_u32 s23, s23, 0
	s_add_u32 s8, s8, 64
	s_addc_u32 s9, s9, 0
	s_cmp_lg_u32 s22, 0x100000
	v_add_u32_e32 v0, 0x840, v0
	s_cbranch_scc1 .LBB0_346
	s_branch .LBB0_335
